# grid barrier: acquire (buffer_inv sc1) issued when the workgroup arrives instead of after the release is observed (overlaps the arrival atomic)
# speedup vs baseline: 1.0001x; 1.0001x over previous
.LBB0_564:
	buffer_inv sc1
	s_mov_b64 s[10:11], exec
	s_lshl_b32 s0, s0, 8
	v_mbcnt_lo_u32_b32 v0, s10, 0
	s_add_u32 s8, s37, s0
	v_readlane_b32 s0, v254, 29
	v_mbcnt_hi_u32_b32 v0, s11, v0
	s_addc_u32 s9, s0, 0
	v_cmp_eq_u32_e32 vcc, 0, v0
	s_and_saveexec_b64 s[74:75], vcc
	s_cbranch_execz .LBB0_566
	s_bcnt1_i32_b64 s0, s[10:11]
	v_mov_b32_e32 v100, s0
	v_mov_b32_e32 v101, 0x1000
	global_atomic_add v100, v101, v100, s[8:9] offset:1024 sc0

.LBB0_579:
	s_or_b64 exec, exec, s[88:89]
	s_waitcnt vmcnt(0)
	s_waitcnt vmcnt(0)

.LBB0_597:
	s_or_b64 exec, exec, s[88:89]
	s_mov_b64 s[74:75], exec
	v_mbcnt_lo_u32_b32 v0, s74, 0
	v_mbcnt_hi_u32_b32 v0, s75, v0
	v_cmp_eq_u32_e32 vcc, 0, v0
	s_waitcnt vmcnt(0)
	s_and_saveexec_b64 s[88:89], vcc
	s_cbranch_execz .LBB0_599
	s_bcnt1_i32_b64 s0, s[74:75]
	v_mov_b32_e32 v0, s0
	v_mov_b32_e32 v98, 0x2000
	global_atomic_add v98, v0, s[8:9] offset:1024

.LBB0_749:
	buffer_inv sc1
	s_lshl_b32 s8, s47, 8
	s_mov_b64 s[10:11], exec
	s_add_u32 s8, s30, s8
	s_addc_u32 s9, s31, 0
	v_mbcnt_lo_u32_b32 v0, s10, 0
	s_add_u32 s8, s8, 0x10000
	v_mbcnt_hi_u32_b32 v0, s11, v0
	s_addc_u32 s9, s9, 0
	v_cmp_eq_u32_e32 vcc, 0, v0
	s_and_saveexec_b64 s[12:13], vcc
	s_cbranch_execz .LBB0_751
	s_bcnt1_i32_b64 s10, s[10:11]
	v_mov_b32_e32 v4, s10
	v_mov_b32_e32 v5, 0x1000
	global_atomic_add v4, v5, v4, s[8:9] offset:1024 sc0

.LBB0_764:
	s_or_b64 exec, exec, s[12:13]
	s_waitcnt vmcnt(0)
	s_waitcnt vmcnt(0)

.LBB0_782:
	s_or_b64 exec, exec, s[10:11]
	s_mov_b64 s[10:11], exec
	v_mbcnt_lo_u32_b32 v0, s10, 0
	v_mbcnt_hi_u32_b32 v0, s11, v0
	v_cmp_eq_u32_e32 vcc, 0, v0
	s_waitcnt vmcnt(0)
	s_and_saveexec_b64 s[12:13], vcc
	s_cbranch_execz .LBB0_784
	s_bcnt1_i32_b64 s10, s[10:11]
	v_mov_b32_e32 v0, s10
	v_mov_b32_e32 v2, 0x2000
	global_atomic_add v2, v0, s[8:9] offset:1024
